# P8: A^T tiles computed once per workgroup (shared through LDS as bf16 operand image) instead of once per value-column wave
# speedup vs baseline: 1.0354x; 1.0173x over previous
.LBB0_906:
	s_cmp_lt_i32 s90, 9
	s_cselect_b64 s[2:3], -1, 0
	s_and_b64 s[38:39], s[2:3], s[0:1]
	s_andn2_b64 vcc, exec, s[38:39]
	s_cbranch_vccnz .LBB0_998
	s_mov_b64 s[70:71], s[62:63]
	s_mov_b32 s68, s59
	s_mov_b64 s[66:67], s[60:61]
	s_cmpk_gt_i32 s58, 0xff
	v_readfirstlane_b32 s20, v0
	s_cbranch_scc1 .LBB0_997
	v_readlane_b32 s15, v251, 48
	v_readfirstlane_b32 s35, v0
	s_lshr_b32 s35, s35, 6
	s_and_b32 s36, s35, 3
	s_lshr_b32 s37, s35, 2
	s_and_b32 s31, s15, 1
	s_bfe_u32 s73, s15, 0x20001
	s_bfe_u32 s74, s15, 0x20003
	s_lshr_b32 s72, s15, 5
	s_lshl_b32 s33, s72, 8
	s_addk_i32 s33, 0x4000
	s_lshl_b32 s34, s72, 11
	s_addk_i32 s34, 0xff00
	s_movk_i32 s48, 0x1800
	s_movk_i32 s49, 0x400
	s_cmp_eq_u32 s31, 0
	s_cselect_b32 s30, s48, s49
	s_lshl_b32 s48, s73, 8
	s_add_u32 s49, s88, 0xa27d000
	s_addc_u32 s52, s89, 0
	s_cmp_eq_u32 s31, 0
	s_cselect_b32 s16, s96, s49
	s_cselect_b32 s17, s97, s52
	s_add_u32 s16, s16, s48
	s_addc_u32 s17, s17, 0
	s_add_u32 s49, s88, 0xb27d000
	s_addc_u32 s52, s89, 0
	s_add_u32 s53, s96, 0x400
	s_addc_u32 s64, s97, 0
	s_cmp_eq_u32 s31, 0
	s_cselect_b32 s18, s53, s49
	s_cselect_b32 s19, s64, s52
	s_add_u32 s18, s18, s48
	s_addc_u32 s19, s19, 0
	s_lshl_b32 s49, s73, 9
	s_lshl_b32 s52, s74, 7
	s_add_i32 s49, s49, s52
	s_add_i32 s52, s49, 0x800
	s_add_u32 s20, s96, s52
	s_addc_u32 s21, s97, 0
	v_readlane_b32 s28, v251, 34
	v_readlane_b32 s29, v251, 35
	s_lshl_b32 s52, s31, 25
	s_add_i32 s52, s52, s49
	s_add_u32 s28, s28, s52
	s_addc_u32 s29, s29, 0
	s_lshl_b32 s49, s31, 3
	s_add_i32 s49, s49, s72
	s_lshl_b32 s49, s49, 2
	s_add_i32 s49, s49, s73
	s_mul_i32 s49, s49, 0x4800
	s_add_u32 s22, s88, 0x115d000
	s_addc_u32 s23, s89, 0
	s_add_u32 s22, s22, s49
	s_addc_u32 s23, s23, 0
	v_bfe_u32 v94, v0, 4, 2
	v_lshrrev_b32_e32 v95, 2, v186
	v_and_b32_e32 v96, 3, v186
	v_mov_b32_e32 v97, 272
	v_mul_u32_u24_e32 v98, v186, v97
	v_lshl_add_u32 v182, v94, 4, v98
	v_lshl_add_u32 v183, v94, 3, v98
	v_mov_b32_e32 v97, 288
	v_mul_u32_u24_e32 v98, v186, v97
	v_lshl_add_u32 v242, v94, 4, v98
	v_lshl_add_u32 v99, v94, 2, v95
	v_mul_u32_u24_e32 v185, v99, v97
	v_lshl_add_u32 v185, v96, 3, v185
	v_mov_b32_e32 v97, 160
	v_mul_u32_u24_e32 v184, v99, v97
	v_lshl_add_u32 v184, v96, 3, v184
	s_lshl_b32 s49, s36, 5
	v_add_u32_e32 v184, s49, v184
	v_lshlrev_b32_e32 v188, 4, v94
	v_add_u32_e32 v188, 0x16800, v188
	v_lshrrev_b32_e32 v95, 4, v0
	v_mov_b32_e32 v97, 272
	v_mul_u32_u24_e32 v189, v95, v97
	v_lshl_add_u32 v189, v186, 4, v189
	v_mov_b32_e32 v97, 288
	v_mul_u32_u24_e32 v243, v95, v97
	v_lshl_add_u32 v243, v186, 4, v243
	v_lshrrev_b32_e32 v96, 3, v0
	v_and_b32_e32 v98, 7, v0
	v_mov_b32_e32 v97, 160
	v_mul_u32_u24_e32 v190, v96, v97
	v_lshl_add_u32 v190, v98, 4, v190
	v_add_u32_e32 v191, 0x16800, v194
	s_cmp_gt_u32 s35, 1
	s_cselect_b32 s52, 0x200, 0
	v_add_u32_e32 v191, s52, v191
	s_cmp_eq_u32 s31, 0
	s_cselect_b64 vcc, -1, 0
	v_sub_u32_e32 v99, 63, v95
	v_cndmask_b32_e32 v99, v99, v95, vcc
	v_mul_lo_u32 v244, v99, s30
	v_lshl_add_u32 v244, v186, 4, v244
	v_add_u32_e32 v95, 32, v95
	v_sub_u32_e32 v99, 63, v95
	v_cndmask_b32_e32 v99, v99, v95, vcc
	v_mul_lo_u32 v245, v99, s30
	v_lshl_add_u32 v245, v186, 4, v245
	v_sub_u32_e32 v99, 63, v96
	v_cndmask_b32_e32 v99, v99, v96, vcc
	v_mov_b32_e32 v97, 0x1800
	v_mul_lo_u32 v246, v99, v97
	v_lshl_add_u32 v246, v98, 4, v246
	v_sub_u32_e32 v99, 15, v186
	v_cndmask_b32_e32 v99, v99, v186, vcc
	v_lshlrev_b32_e32 v247, 11, v99
	v_lshl_add_u32 v247, v94, 3, v247
	v_add_u32_e32 v247, s49, v247
	v_lshlrev_b32_e32 v95, 2, v94
	s_lshl_b32 s52, s35, 1
	s_lshr_b32 s75, 0xa90f, s52
	s_and_b32 s75, s75, 3
	s_lshr_b32 s98, 0xa008, s52
	s_and_b32 s98, s98, 3
	s_lshr_b32 s99, 0xa50d, s52
	s_and_b32 s99, s99, 3
	v_cmp_gt_u32_e64 s[92:93], v95, v186
	s_nop 1
	s_cmp_eq_u32 s98, s75
	s_cselect_b64 s[40:41], s[92:93], 0
	s_cmp_eq_u32 s99, s75
	s_cselect_b64 s[80:81], s[92:93], 0
	v_add_u32_e32 v96, 1, v95
	v_cmp_gt_u32_e64 s[92:93], v96, v186
	s_nop 1
	s_cmp_eq_u32 s98, s75
	s_cselect_b64 s[42:43], s[92:93], 0
	s_cmp_eq_u32 s99, s75
	s_cselect_b64 s[82:83], s[92:93], 0
	v_add_u32_e32 v96, 2, v95
	v_cmp_gt_u32_e64 s[92:93], v96, v186
	s_nop 1
	s_cmp_eq_u32 s98, s75
	s_cselect_b64 s[44:45], s[92:93], 0
	s_cmp_eq_u32 s99, s75
	s_cselect_b64 s[84:85], s[92:93], 0
	v_add_u32_e32 v96, 3, v95
	v_cmp_gt_u32_e64 s[92:93], v96, v186
	s_nop 1
	s_cmp_eq_u32 s98, s75
	s_cselect_b64 s[46:47], s[92:93], 0
	s_cmp_eq_u32 s99, s75
	s_cselect_b64 s[86:87], s[92:93], 0
	s_mul_i32 s52, s98, 4608
	v_add_u32_e32 v54, s52, v242
	s_mul_i32 s52, s99, 4608
	v_add_u32_e32 v55, s52, v242
	s_mul_i32 s52, s75, 4352
	v_add_u32_e32 v56, s52, v182
	v_mov_b32_e32 v97, 160
	v_mul_u32_u24_e32 v59, v186, v97
	v_lshl_add_u32 v59, v94, 4, v59
	v_add_u32_e32 v59, 0x17800, v59
	s_mul_i32 s52, s75, 2560
	s_lshr_b32 s53, s98, 1
	s_lshl_b32 s53, s53, 6
	s_add_i32 s53, s53, s52
	s_and_b32 s64, s98, 1
	s_lshl_b32 s64, s64, 3
	s_add_i32 s53, s53, s64
	v_add_u32_e32 v57, s53, v59
	s_lshr_b32 s53, s99, 1
	s_lshl_b32 s53, s53, 6
	s_add_i32 s53, s53, s52
	s_and_b32 s64, s99, 1
	s_lshl_b32 s64, s64, 3
	s_add_i32 s53, s53, s64
	v_add_u32_e32 v58, s53, v59
	v_lshlrev_b32_e32 v96, 4, v0
	v_add_u32_e32 v96, 0x17800, v96
	v_mov_b32_e32 v42, 0
	v_mov_b32_e32 v43, 0
	v_mov_b32_e32 v44, 0
	v_mov_b32_e32 v45, 0
	ds_write_b128 v96, v[42:45]
	ds_write_b128 v96, v[42:45] offset:8192
	v_mov_b32_e32 v2, 0
	v_mov_b32_e32 v3, 0
	v_mov_b32_e32 v4, 0
	v_mov_b32_e32 v5, 0
	v_mov_b32_e32 v6, 0
	v_mov_b32_e32 v7, 0
	v_mov_b32_e32 v8, 0
	v_mov_b32_e32 v9, 0
	v_mov_b32_e32 v10, 0
	v_mov_b32_e32 v11, 0
	v_mov_b32_e32 v12, 0
	v_mov_b32_e32 v13, 0
	v_mov_b32_e32 v14, 0
	v_mov_b32_e32 v15, 0
	v_mov_b32_e32 v16, 0
	v_mov_b32_e32 v17, 0
	v_mov_b32_e32 v18, 0
	v_mov_b32_e32 v19, 0
	v_mov_b32_e32 v20, 0
	v_mov_b32_e32 v21, 0
	v_mov_b32_e32 v22, 0
	v_mov_b32_e32 v23, 0
	v_mov_b32_e32 v24, 0
	v_mov_b32_e32 v25, 0
	v_mov_b32_e32 v26, 0
	v_mov_b32_e32 v27, 0
	v_mov_b32_e32 v28, 0
	v_mov_b32_e32 v29, 0
	v_mov_b32_e32 v30, 0
	v_mov_b32_e32 v31, 0
	v_mov_b32_e32 v32, 0
	v_mov_b32_e32 v33, 0
	v_add_u32_e32 v182, 0xb400, v182
	v_add_u32_e32 v183, 0xb400, v183
	v_add_u32_e32 v184, 0xb400, v184
	v_add_u32_e32 v185, 0xb400, v185
	v_add_u32_e32 v242, 0xb400, v242
	v_add_u32_e32 v54, 0xb400, v54
	v_add_u32_e32 v55, 0xb400, v55
	v_add_u32_e32 v56, 0xb400, v56
	v_add_u32_e32 v188, 0x200, v188
	s_mov_b32 s64, 0
	s_min_u32 s65, s64, 35
	s_sub_i32 s48, 3, s65
	s_sub_i32 s49, 39, s65
	s_cmp_lt_u32 s65, 4
	s_cselect_b32 s48, s48, s49
	s_cmp_eq_u32 s31, 0
	s_cselect_b32 s54, s65, s48
	s_lshl_b32 s48, s54, 6
	s_add_i32 s49, s33, s48
	s_add_i32 s48, s34, s48
	s_cmp_lt_u32 s54, 4
	s_cselect_b32 s55, s49, s48
	s_mul_i32 s48, s55, s30
	s_add_u32 s0, s16, s48
	s_addc_u32 s1, s17, 0
	s_add_u32 s2, s18, s48
	s_addc_u32 s3, s19, 0
	s_mul_i32 s48, s55, 0x1800
	s_add_u32 s4, s20, s48
	s_addc_u32 s5, s21, 0
	s_lshl_b32 s48, s54, 9
	s_add_u32 s6, s22, s48
	s_addc_u32 s7, s23, 0
	global_load_dwordx4 v[224:227], v244, s[2:3]
	global_load_dwordx4 v[228:231], v245, s[2:3]
	global_load_dwordx4 v[232:235], v246, s[4:5]
	global_load_dwordx4 v[216:219], v244, s[0:1]
	global_load_dwordx4 v[220:223], v245, s[0:1]
	global_load_dword v236, v194, s[6:7]
	s_mov_b32 s64, 1
	s_min_u32 s65, s64, 35
	s_sub_i32 s48, 3, s65
	s_sub_i32 s49, 39, s65
	s_cmp_lt_u32 s65, 4
	s_cselect_b32 s48, s48, s49
	s_cmp_eq_u32 s31, 0
	s_cselect_b32 s54, s65, s48
	s_lshl_b32 s48, s54, 6
	s_add_i32 s49, s33, s48
	s_add_i32 s48, s34, s48
	s_cmp_lt_u32 s54, 4
	s_cselect_b32 s55, s49, s48
	s_mul_i32 s48, s55, s30
	s_add_u32 s0, s16, s48
	s_addc_u32 s1, s17, 0
	s_add_u32 s2, s18, s48
	s_addc_u32 s3, s19, 0
	s_mul_i32 s48, s55, 0x1800
	s_add_u32 s4, s20, s48
	s_addc_u32 s5, s21, 0
	s_lshl_b32 s48, s54, 9
	s_add_u32 s6, s22, s48
	s_addc_u32 s7, s23, 0
	global_load_dwordx4 v[142:145], v244, s[2:3]
	global_load_dwordx4 v[146:149], v245, s[2:3]
	global_load_dwordx4 v[238:241], v246, s[4:5]
	global_load_dwordx4 v[134:137], v244, s[0:1]
	global_load_dwordx4 v[138:141], v245, s[0:1]
	global_load_dword v237, v194, s[6:7]
	s_waitcnt vmcnt(6)
	ds_write_b128 v243, v[224:227] offset:17408
	ds_write_b128 v243, v[228:231] offset:26624
	ds_write_b128 v190, v[232:235] offset:35840
	ds_write_b128 v189, v[216:219]
	ds_write_b128 v189, v[220:223] offset:8704
	ds_write_b32 v191, v236
	s_mov_b32 s64, 2
	s_min_u32 s65, s64, 35
	s_sub_i32 s48, 3, s65
	s_sub_i32 s49, 39, s65
	s_cmp_lt_u32 s65, 4
	s_cselect_b32 s48, s48, s49
	s_cmp_eq_u32 s31, 0
	s_cselect_b32 s54, s65, s48
	s_lshl_b32 s48, s54, 6
	s_add_i32 s49, s33, s48
	s_add_i32 s48, s34, s48
	s_cmp_lt_u32 s54, 4
	s_cselect_b32 s55, s49, s48
	s_mul_i32 s48, s55, s30
	s_add_u32 s0, s16, s48
	s_addc_u32 s1, s17, 0
	s_add_u32 s2, s18, s48
	s_addc_u32 s3, s19, 0
	s_mul_i32 s48, s55, 0x1800
	s_add_u32 s4, s20, s48
	s_addc_u32 s5, s21, 0
	s_lshl_b32 s48, s54, 9
	s_add_u32 s6, s22, s48
	s_addc_u32 s7, s23, 0
	global_load_dwordx4 v[224:227], v244, s[2:3]
	global_load_dwordx4 v[228:231], v245, s[2:3]
	global_load_dwordx4 v[232:235], v246, s[4:5]
	global_load_dwordx4 v[216:219], v244, s[0:1]
	global_load_dwordx4 v[220:223], v245, s[0:1]
	global_load_dword v236, v194, s[6:7]
	s_mov_b32 s12, 0
	s_waitcnt lgkmcnt(0)
	s_barrier
.Lp8_step:
	v_add_u32_e32 v182, 0xffff4c00, v182
	v_add_u32_e32 v183, 0xffff4c00, v183
	v_add_u32_e32 v184, 0xffff4c00, v184
	v_add_u32_e32 v185, 0xffff4c00, v185
	v_add_u32_e32 v242, 0xffff4c00, v242
	v_add_u32_e32 v54, 0xffff4c00, v54
	v_add_u32_e32 v55, 0xffff4c00, v55
	v_add_u32_e32 v56, 0xffff4c00, v56
	v_add_u32_e32 v189, 0xb400, v189
	v_add_u32_e32 v243, 0xb400, v243
	v_add_u32_e32 v190, 0xb400, v190
	v_add_u32_e32 v188, 0xfffffe00, v188
	v_add_u32_e32 v191, 0x200, v191
	s_cmp_lt_u32 s12, 4
	s_nop 0
	s_cbranch_scc0 .Lp8_lat_0
	ds_read_b64_tr_b16 v[126:127], v184 offset:35840
	ds_read_b64_tr_b16 v[128:129], v184 offset:38400
	ds_read_b64_tr_b16 v[130:131], v184 offset:40960
	ds_read_b64_tr_b16 v[132:133], v184 offset:43520
	ds_read_b64_tr_b16 v[62:63], v185 offset:17408
	ds_read_b64_tr_b16 v[64:65], v185 offset:22016
	ds_read_b64_tr_b16 v[66:67], v185 offset:26624
	ds_read_b64_tr_b16 v[68:69], v185 offset:31232
	ds_read_b64_tr_b16 v[70:71], v185 offset:17440
	ds_read_b64_tr_b16 v[72:73], v185 offset:22048
	ds_read_b64_tr_b16 v[74:75], v185 offset:26656
	ds_read_b64_tr_b16 v[76:77], v185 offset:31264
	ds_read_b64_tr_b16 v[78:79], v185 offset:17472
	ds_read_b64_tr_b16 v[80:81], v185 offset:22080
	ds_read_b64_tr_b16 v[82:83], v185 offset:26688
	ds_read_b64_tr_b16 v[84:85], v185 offset:31296
	ds_read_b64_tr_b16 v[86:87], v185 offset:17504
	ds_read_b64_tr_b16 v[88:89], v185 offset:22112
	ds_read_b64_tr_b16 v[90:91], v185 offset:26720
	ds_read_b64_tr_b16 v[92:93], v185 offset:31328
	ds_read_b64_tr_b16 v[94:95], v185 offset:17536
	ds_read_b64_tr_b16 v[96:97], v185 offset:22144
	ds_read_b64_tr_b16 v[98:99], v185 offset:26752
	ds_read_b64_tr_b16 v[100:101], v185 offset:31360
	ds_read_b64_tr_b16 v[102:103], v185 offset:17568
	ds_read_b64_tr_b16 v[104:105], v185 offset:22176
	ds_read_b64_tr_b16 v[106:107], v185 offset:26784
	ds_read_b64_tr_b16 v[108:109], v185 offset:31392
	ds_read_b64_tr_b16 v[110:111], v185 offset:17600
	ds_read_b64_tr_b16 v[112:113], v185 offset:22208
	ds_read_b64_tr_b16 v[114:115], v185 offset:26816
	ds_read_b64_tr_b16 v[116:117], v185 offset:31424
	ds_read_b64_tr_b16 v[118:119], v185 offset:17632
	ds_read_b64_tr_b16 v[120:121], v185 offset:22240
	ds_read_b64_tr_b16 v[122:123], v185 offset:26848
	ds_read_b64_tr_b16 v[124:125], v185 offset:31456
	ds_read_b128 v[166:169], v188 offset:0
	ds_read_b128 v[170:173], v188 offset:64
	ds_read_b128 v[174:177], v188 offset:128
	ds_read_b128 v[178:181], v188 offset:192
	ds_read_b128 v[200:203], v188 offset:256
	ds_read_b128 v[204:207], v188 offset:320
	ds_read_b128 v[208:211], v188 offset:384
	ds_read_b128 v[212:215], v188 offset:448
	s_waitcnt vmcnt(6)
	ds_write_b128 v243, v[142:145] offset:17408
	ds_write_b128 v243, v[146:149] offset:26624
	ds_write_b128 v190, v[238:241] offset:35840
	ds_write_b128 v189, v[134:137]
	ds_write_b128 v189, v[138:141] offset:8704
	ds_write_b32 v191, v237
	s_add_i32 s64, s12, 3
	s_min_u32 s65, s64, 35
	s_sub_i32 s48, 3, s65
	s_sub_i32 s49, 39, s65
	s_cmp_lt_u32 s65, 4
	s_cselect_b32 s48, s48, s49
	s_cmp_eq_u32 s31, 0
	s_cselect_b32 s54, s65, s48
	s_lshl_b32 s48, s54, 6
	s_add_i32 s49, s33, s48
	s_add_i32 s48, s34, s48
	s_cmp_lt_u32 s54, 4
	s_cselect_b32 s55, s49, s48
	s_mul_i32 s48, s55, s30
	s_add_u32 s0, s16, s48
	s_addc_u32 s1, s17, 0
	s_add_u32 s2, s18, s48
	s_addc_u32 s3, s19, 0
	s_mul_i32 s48, s55, 0x1800
	s_add_u32 s4, s20, s48
	s_addc_u32 s5, s21, 0
	s_lshl_b32 s48, s54, 9
	s_add_u32 s6, s22, s48
	s_addc_u32 s7, s23, 0
	global_load_dwordx4 v[142:145], v244, s[2:3]
	global_load_dwordx4 v[146:149], v245, s[2:3]
	global_load_dwordx4 v[238:241], v246, s[4:5]
	global_load_dwordx4 v[134:137], v244, s[0:1]
	global_load_dwordx4 v[138:141], v245, s[0:1]
	global_load_dword v237, v194, s[6:7]
	s_waitcnt lgkmcnt(15)
	v_mfma_f32_16x16x32_bf16 v[2:5], v[62:65], v[126:129], v[2:5]
	v_mfma_f32_16x16x32_bf16 v[2:5], v[66:69], v[130:133], v[2:5]
	v_mfma_f32_16x16x32_bf16 v[6:9], v[70:73], v[126:129], v[6:9]
	v_mfma_f32_16x16x32_bf16 v[6:9], v[74:77], v[130:133], v[6:9]
	v_mfma_f32_16x16x32_bf16 v[10:13], v[78:81], v[126:129], v[10:13]
	v_mfma_f32_16x16x32_bf16 v[10:13], v[82:85], v[130:133], v[10:13]
	v_mfma_f32_16x16x32_bf16 v[14:17], v[86:89], v[126:129], v[14:17]
	v_mfma_f32_16x16x32_bf16 v[14:17], v[90:93], v[130:133], v[14:17]
	s_waitcnt lgkmcnt(14)
	v_mfma_f32_16x16x32_bf16 v[18:21], v[94:97], v[126:129], v[18:21]
	v_mfma_f32_16x16x32_bf16 v[18:21], v[98:101], v[130:133], v[18:21]
	v_mfma_f32_16x16x32_bf16 v[22:25], v[102:105], v[126:129], v[22:25]
	v_mfma_f32_16x16x32_bf16 v[22:25], v[106:109], v[130:133], v[22:25]
	v_mfma_f32_16x16x32_bf16 v[26:29], v[110:113], v[126:129], v[26:29]
	v_mfma_f32_16x16x32_bf16 v[26:29], v[114:117], v[130:133], v[26:29]
	v_mfma_f32_16x16x32_bf16 v[30:33], v[118:121], v[126:129], v[30:33]
	v_mfma_f32_16x16x32_bf16 v[30:33], v[122:125], v[130:133], v[30:33]
	s_waitcnt lgkmcnt(0)
	v_pk_mul_f32 v[2:3], v[2:3], v[166:167]
	v_pk_mul_f32 v[4:5], v[4:5], v[168:169]
	v_pk_mul_f32 v[6:7], v[6:7], v[170:171]
	v_pk_mul_f32 v[8:9], v[8:9], v[172:173]
	v_pk_mul_f32 v[10:11], v[10:11], v[174:175]
	v_pk_mul_f32 v[12:13], v[12:13], v[176:177]
	v_pk_mul_f32 v[14:15], v[14:15], v[178:179]
	v_pk_mul_f32 v[16:17], v[16:17], v[180:181]
	v_pk_mul_f32 v[18:19], v[18:19], v[200:201]
	v_pk_mul_f32 v[20:21], v[20:21], v[202:203]
	v_pk_mul_f32 v[22:23], v[22:23], v[204:205]
	v_pk_mul_f32 v[24:25], v[24:25], v[206:207]
	v_pk_mul_f32 v[26:27], v[26:27], v[208:209]
	v_pk_mul_f32 v[28:29], v[28:29], v[210:211]
	v_pk_mul_f32 v[30:31], v[30:31], v[212:213]
	v_pk_mul_f32 v[32:33], v[32:33], v[214:215]
	s_nop 1
	s_barrier
	s_branch .Lp8_next_0
.Lp8_lat_0:
	s_cmp_eq_u32 s37, 0
	s_cbranch_scc0 .Lp8_lat1_0
	s_sub_i32 s48, 3, s12
	s_sub_i32 s49, 39, s12
	s_cmp_lt_u32 s12, 4
	s_cselect_b32 s48, s48, s49
	s_cmp_eq_u32 s31, 0
	s_cselect_b32 s54, s12, s48
	s_lshl_b32 s48, s54, 6
	s_add_i32 s49, s33, s48
	s_add_i32 s48, s34, s48
	s_cmp_lt_u32 s54, 4
	s_cselect_b32 s55, s49, s48
	s_add_i32 s48, s55, 0
	s_add_i32 s49, s55, 48
	s_cmp_eq_u32 s31, 0
	s_cselect_b32 s48, s48, s49
	s_lshl_b32 s48, s48, 11
	s_add_u32 s8, s28, s48
	s_addc_u32 s9, s29, 0
	s_add_i32 s48, s55, 48
	s_add_i32 s49, s55, 0
	s_cmp_eq_u32 s31, 0
	s_cselect_b32 s48, s48, s49
	s_lshl_b32 s48, s48, 11
	s_add_u32 s10, s28, s48
	s_addc_u32 s11, s29, 0
	v_cvt_pk_bf16_f32 v150, v2, v3
	v_cvt_pk_bf16_f32 v151, v4, v5
	v_cvt_pk_bf16_f32 v152, v6, v7
	v_cvt_pk_bf16_f32 v153, v8, v9
	v_cvt_pk_bf16_f32 v154, v10, v11
	v_cvt_pk_bf16_f32 v155, v12, v13
	v_cvt_pk_bf16_f32 v156, v14, v15
	v_cvt_pk_bf16_f32 v157, v16, v17
	v_cvt_pk_bf16_f32 v158, v18, v19
	v_cvt_pk_bf16_f32 v159, v20, v21
	v_cvt_pk_bf16_f32 v160, v22, v23
	v_cvt_pk_bf16_f32 v161, v24, v25
	v_cvt_pk_bf16_f32 v162, v26, v27
	v_cvt_pk_bf16_f32 v163, v28, v29
	v_cvt_pk_bf16_f32 v164, v30, v31
	v_cvt_pk_bf16_f32 v165, v32, v33
	ds_read_b64_tr_b16 v[126:127], v184 offset:35840
	ds_read_b64_tr_b16 v[128:129], v184 offset:38400
	ds_read_b64_tr_b16 v[130:131], v184 offset:40960
	ds_read_b64_tr_b16 v[132:133], v184 offset:43520
	ds_read_b64_tr_b16 v[62:63], v185 offset:17408
	ds_read_b64_tr_b16 v[64:65], v185 offset:22016
	ds_read_b64_tr_b16 v[66:67], v185 offset:26624
	ds_read_b64_tr_b16 v[68:69], v185 offset:31232
	ds_read_b64_tr_b16 v[70:71], v185 offset:17440
	ds_read_b64_tr_b16 v[72:73], v185 offset:22048
	ds_read_b64_tr_b16 v[74:75], v185 offset:26656
	ds_read_b64_tr_b16 v[76:77], v185 offset:31264
	ds_read_b64_tr_b16 v[78:79], v185 offset:17472
	ds_read_b64_tr_b16 v[80:81], v185 offset:22080
	ds_read_b64_tr_b16 v[82:83], v185 offset:26688
	ds_read_b64_tr_b16 v[84:85], v185 offset:31296
	ds_read_b64_tr_b16 v[86:87], v185 offset:17504
	ds_read_b64_tr_b16 v[88:89], v185 offset:22112
	ds_read_b64_tr_b16 v[90:91], v185 offset:26720
	ds_read_b64_tr_b16 v[92:93], v185 offset:31328
	ds_read_b64 v[94:95], v183 offset:0
	ds_read_b64 v[96:97], v183 offset:32
	ds_read_b64 v[98:99], v183 offset:64
	ds_read_b64 v[100:101], v183 offset:96
	ds_read_b64 v[102:103], v183 offset:128
	ds_read_b64 v[104:105], v183 offset:160
	ds_read_b64 v[106:107], v183 offset:192
	ds_read_b64 v[108:109], v183 offset:224
	ds_read_b64 v[110:111], v183 offset:13056
	ds_read_b64 v[112:113], v183 offset:13088
	ds_read_b64 v[114:115], v183 offset:13120
	ds_read_b64 v[116:117], v183 offset:13152
	ds_read_b64 v[118:119], v183 offset:13184
	ds_read_b64 v[120:121], v183 offset:13216
	ds_read_b64 v[122:123], v183 offset:13248
	ds_read_b64 v[124:125], v183 offset:13280
	s_waitcnt lgkmcnt(15)
	v_mfma_f32_16x16x32_bf16 v[2:5], v[62:65], v[126:129], v[2:5]
	v_mfma_f32_16x16x32_bf16 v[2:5], v[66:69], v[130:133], v[2:5]
	v_mfma_f32_16x16x32_bf16 v[6:9], v[70:73], v[126:129], v[6:9]
	v_mfma_f32_16x16x32_bf16 v[6:9], v[74:77], v[130:133], v[6:9]
	v_mfma_f32_16x16x32_bf16 v[10:13], v[78:81], v[126:129], v[10:13]
	v_mfma_f32_16x16x32_bf16 v[10:13], v[82:85], v[130:133], v[10:13]
	v_mfma_f32_16x16x32_bf16 v[14:17], v[86:89], v[126:129], v[14:17]
	v_mfma_f32_16x16x32_bf16 v[14:17], v[90:93], v[130:133], v[14:17]
	s_waitcnt lgkmcnt(0)
	v_mfma_f32_16x16x32_bf16 v[34:37], v[150:153], v[94:97], 0
	v_mfma_f32_16x16x32_bf16 v[38:41], v[150:153], v[110:113], 0
	v_mfma_f32_16x16x32_bf16 v[34:37], v[154:157], v[98:101], v[34:37]
	v_mfma_f32_16x16x32_bf16 v[38:41], v[154:157], v[114:117], v[38:41]
	v_mfma_f32_16x16x32_bf16 v[34:37], v[158:161], v[102:105], v[34:37]
	v_mfma_f32_16x16x32_bf16 v[38:41], v[158:161], v[118:121], v[38:41]
	v_mfma_f32_16x16x32_bf16 v[34:37], v[162:165], v[106:109], v[34:37]
	v_mfma_f32_16x16x32_bf16 v[38:41], v[162:165], v[122:125], v[38:41]
	s_nop 7
	s_barrier
	ds_read_b128 v[62:65], v56 offset:0
	ds_read_b128 v[66:69], v56 offset:64
	ds_read_b128 v[70:73], v56 offset:128
	ds_read_b128 v[74:77], v56 offset:192
	ds_read_b128 v[166:169], v54 offset:17408
	ds_read_b128 v[170:173], v54 offset:17472
	ds_read_b128 v[174:177], v54 offset:17536
	ds_read_b128 v[178:181], v54 offset:17600
	ds_read_b128 v[200:203], v55 offset:17408
	ds_read_b128 v[204:207], v55 offset:17472
	ds_read_b128 v[208:211], v55 offset:17536
	ds_read_b128 v[212:215], v55 offset:17600
	s_cmp_gt_u32 s12, 5
	s_cbranch_scc1 .Lp8_w10_2
	s_waitcnt vmcnt(6)
	s_branch .Lp8_wd_2

.Lp8_wd_2:
	ds_write_b128 v243, v[142:145] offset:17408
	ds_write_b128 v243, v[146:149] offset:26624
	ds_write_b128 v190, v[238:241] offset:35840
	ds_write_b128 v189, v[134:137]
	ds_write_b128 v189, v[138:141] offset:8704
	ds_write_b32 v191, v237
	s_add_i32 s64, s12, 3
	s_min_u32 s65, s64, 35
	s_sub_i32 s48, 3, s65
	s_sub_i32 s49, 39, s65
	s_cmp_lt_u32 s65, 4
	s_cselect_b32 s48, s48, s49
	s_cmp_eq_u32 s31, 0
	s_cselect_b32 s54, s65, s48
	s_lshl_b32 s48, s54, 6
	s_add_i32 s49, s33, s48
	s_add_i32 s48, s34, s48
	s_cmp_lt_u32 s54, 4
	s_cselect_b32 s55, s49, s48
	s_mul_i32 s48, s55, s30
	s_add_u32 s0, s16, s48
	s_addc_u32 s1, s17, 0
	s_add_u32 s2, s18, s48
	s_addc_u32 s3, s19, 0
	s_mul_i32 s48, s55, 0x1800
	s_add_u32 s4, s20, s48
	s_addc_u32 s5, s21, 0
	s_lshl_b32 s48, s54, 9
	s_add_u32 s6, s22, s48
	s_addc_u32 s7, s23, 0
	global_load_dwordx4 v[142:145], v244, s[2:3]
	global_load_dwordx4 v[146:149], v245, s[2:3]
	global_load_dwordx4 v[238:241], v246, s[4:5]
	global_load_dwordx4 v[134:137], v244, s[0:1]
	global_load_dwordx4 v[138:141], v245, s[0:1]
	global_load_dword v237, v194, s[6:7]
	s_waitcnt lgkmcnt(6)
	v_mfma_f32_16x16x32_bf16 v[42:45], v[166:169], v[62:65], 0
	v_mfma_f32_16x16x32_bf16 v[46:49], v[200:203], v[62:65], 0
	v_mfma_f32_16x16x32_bf16 v[42:45], v[170:173], v[66:69], v[42:45]
	v_mfma_f32_16x16x32_bf16 v[46:49], v[204:207], v[66:69], v[46:49]
	v_mfma_f32_16x16x32_bf16 v[42:45], v[174:177], v[70:73], v[42:45]
	v_mfma_f32_16x16x32_bf16 v[46:49], v[208:211], v[70:73], v[46:49]
	v_mfma_f32_16x16x32_bf16 v[42:45], v[178:181], v[74:77], v[42:45]
	v_mfma_f32_16x16x32_bf16 v[46:49], v[212:215], v[74:77], v[46:49]
	s_nop 6
	v_cndmask_b32_e64 v42, v42, 0, s[40:41]
	v_cndmask_b32_e64 v43, v43, 0, s[42:43]
	v_cndmask_b32_e64 v44, v44, 0, s[44:45]
	v_cndmask_b32_e64 v45, v45, 0, s[46:47]
	v_cndmask_b32_e64 v46, v46, 0, s[80:81]
	v_cndmask_b32_e64 v47, v47, 0, s[82:83]
	v_cndmask_b32_e64 v48, v48, 0, s[84:85]
	v_cndmask_b32_e64 v49, v49, 0, s[86:87]
	v_cvt_pk_bf16_f32 v50, v42, v43
	v_cvt_pk_bf16_f32 v51, v44, v45
	v_cvt_pk_bf16_f32 v52, v46, v47
	v_cvt_pk_bf16_f32 v53, v48, v49
	ds_write_b64 v57, v[50:51]
	ds_write_b64 v58, v[52:53]
	s_waitcnt lgkmcnt(0)
	s_barrier
	ds_read_b64_tr_b16 v[62:63], v185 offset:17536
	ds_read_b64_tr_b16 v[64:65], v185 offset:22144
	ds_read_b64_tr_b16 v[66:67], v185 offset:26752
	ds_read_b64_tr_b16 v[68:69], v185 offset:31360
	ds_read_b64_tr_b16 v[70:71], v185 offset:17568
	ds_read_b64_tr_b16 v[72:73], v185 offset:22176
	ds_read_b64_tr_b16 v[74:75], v185 offset:26784
	ds_read_b64_tr_b16 v[76:77], v185 offset:31392
	ds_read_b64_tr_b16 v[78:79], v185 offset:17600
	ds_read_b64_tr_b16 v[80:81], v185 offset:22208
	ds_read_b64_tr_b16 v[82:83], v185 offset:26816
	ds_read_b64_tr_b16 v[84:85], v185 offset:31424
	ds_read_b64_tr_b16 v[86:87], v185 offset:17632
	ds_read_b64_tr_b16 v[88:89], v185 offset:22240
	ds_read_b64_tr_b16 v[90:91], v185 offset:26848
	ds_read_b64_tr_b16 v[92:93], v185 offset:31456
	ds_read_b128 v[150:153], v59 offset:0
	ds_read_b128 v[154:157], v59 offset:7680
	ds_read_b128 v[158:161], v59 offset:7744
	ds_read_b128 v[166:169], v188 offset:0
	ds_read_b128 v[170:173], v188 offset:64
	ds_read_b128 v[174:177], v188 offset:128
	ds_read_b128 v[178:181], v188 offset:192
	ds_read_b128 v[200:203], v188 offset:256
	ds_read_b128 v[204:207], v188 offset:320
	ds_read_b128 v[208:211], v188 offset:384
	ds_read_b128 v[212:215], v188 offset:448
	s_waitcnt lgkmcnt(11)
	v_mfma_f32_16x16x32_bf16 v[18:21], v[62:65], v[126:129], v[18:21]
	v_mfma_f32_16x16x32_bf16 v[18:21], v[66:69], v[130:133], v[18:21]
	v_mfma_f32_16x16x32_bf16 v[22:25], v[70:73], v[126:129], v[22:25]
	v_mfma_f32_16x16x32_bf16 v[22:25], v[74:77], v[130:133], v[22:25]
	v_mfma_f32_16x16x32_bf16 v[26:29], v[78:81], v[126:129], v[26:29]
	v_mfma_f32_16x16x32_bf16 v[26:29], v[82:85], v[130:133], v[26:29]
	v_mfma_f32_16x16x32_bf16 v[30:33], v[86:89], v[126:129], v[30:33]
	v_mfma_f32_16x16x32_bf16 v[30:33], v[90:93], v[130:133], v[30:33]
	s_waitcnt lgkmcnt(8)
	v_mfma_f32_16x16x32_bf16 v[34:37], v[126:129], v[150:153], v[34:37]
	v_mfma_f32_16x16x32_bf16 v[38:41], v[126:129], v[154:157], v[38:41]
	v_mfma_f32_16x16x32_bf16 v[38:41], v[130:133], v[158:161], v[38:41]
	s_waitcnt lgkmcnt(0)
	v_pk_mul_f32 v[2:3], v[2:3], v[166:167]
	v_pk_mul_f32 v[4:5], v[4:5], v[168:169]
	v_pk_mul_f32 v[6:7], v[6:7], v[170:171]
	v_pk_mul_f32 v[8:9], v[8:9], v[172:173]
	v_pk_mul_f32 v[10:11], v[10:11], v[174:175]
	v_pk_mul_f32 v[12:13], v[12:13], v[176:177]
	v_pk_mul_f32 v[14:15], v[14:15], v[178:179]
	v_pk_mul_f32 v[16:17], v[16:17], v[180:181]
	v_pk_mul_f32 v[18:19], v[18:19], v[200:201]
	v_pk_mul_f32 v[20:21], v[20:21], v[202:203]
	v_pk_mul_f32 v[22:23], v[22:23], v[204:205]
	v_pk_mul_f32 v[24:25], v[24:25], v[206:207]
	v_pk_mul_f32 v[26:27], v[26:27], v[208:209]
	v_pk_mul_f32 v[28:29], v[28:29], v[210:211]
	v_pk_mul_f32 v[30:31], v[30:31], v[212:213]
	v_pk_mul_f32 v[32:33], v[32:33], v[214:215]
	v_cvt_pk_bf16_f32 v50, v34, v35
	v_cvt_pk_bf16_f32 v51, v36, v37
	global_store_dwordx2 v247, v[50:51], s[8:9]
	v_cvt_pk_bf16_f32 v52, v38, v39
	v_cvt_pk_bf16_f32 v53, v40, v41
	global_store_dwordx2 v247, v[52:53], s[10:11]
	s_nop 0
	s_barrier
	s_branch .Lp8_next_0
.Lp8_lat1_0:
	s_cmp_eq_u32 s12, 4
	s_cbranch_scc1 .Lp8_first_3
	ds_read_b128 v[150:153], v59 offset:2560
	ds_read_b128 v[154:157], v59 offset:5120
	ds_read_b128 v[158:161], v59 offset:5184
	s_waitcnt lgkmcnt(11)
	v_mfma_f32_16x16x32_bf16 v[18:21], v[62:65], v[126:129], v[18:21]
	v_mfma_f32_16x16x32_bf16 v[18:21], v[66:69], v[130:133], v[18:21]
	v_mfma_f32_16x16x32_bf16 v[22:25], v[70:73], v[126:129], v[22:25]
	v_mfma_f32_16x16x32_bf16 v[22:25], v[74:77], v[130:133], v[22:25]
	v_mfma_f32_16x16x32_bf16 v[26:29], v[78:81], v[126:129], v[26:29]
	v_mfma_f32_16x16x32_bf16 v[26:29], v[82:85], v[130:133], v[26:29]
	v_mfma_f32_16x16x32_bf16 v[30:33], v[86:89], v[126:129], v[30:33]
	v_mfma_f32_16x16x32_bf16 v[30:33], v[90:93], v[130:133], v[30:33]
	s_waitcnt lgkmcnt(0)
	v_mfma_f32_16x16x32_bf16 v[34:37], v[126:129], v[150:153], v[34:37]
	v_mfma_f32_16x16x32_bf16 v[38:41], v[126:129], v[154:157], v[38:41]
	v_mfma_f32_16x16x32_bf16 v[38:41], v[130:133], v[158:161], v[38:41]
	v_pk_mul_f32 v[2:3], v[2:3], v[166:167]
	v_pk_mul_f32 v[4:5], v[4:5], v[168:169]
	v_pk_mul_f32 v[6:7], v[6:7], v[170:171]
	v_pk_mul_f32 v[8:9], v[8:9], v[172:173]
	v_pk_mul_f32 v[10:11], v[10:11], v[174:175]
	v_pk_mul_f32 v[12:13], v[12:13], v[176:177]
	v_pk_mul_f32 v[14:15], v[14:15], v[178:179]
	v_pk_mul_f32 v[16:17], v[16:17], v[180:181]
	v_pk_mul_f32 v[18:19], v[18:19], v[200:201]
	v_pk_mul_f32 v[20:21], v[20:21], v[202:203]
	v_pk_mul_f32 v[22:23], v[22:23], v[204:205]
	v_pk_mul_f32 v[24:25], v[24:25], v[206:207]
	v_pk_mul_f32 v[26:27], v[26:27], v[208:209]
	v_pk_mul_f32 v[28:29], v[28:29], v[210:211]
	v_pk_mul_f32 v[30:31], v[30:31], v[212:213]
	v_pk_mul_f32 v[32:33], v[32:33], v[214:215]
	v_cvt_pk_bf16_f32 v50, v34, v35
	v_cvt_pk_bf16_f32 v51, v36, v37
	global_store_dwordx2 v247, v[50:51], s[76:77]
	v_cvt_pk_bf16_f32 v52, v38, v39
	v_cvt_pk_bf16_f32 v53, v40, v41
	global_store_dwordx2 v247, v[52:53], s[78:79]
	s_nop 0
.Lp8_first_3:
	s_sub_i32 s48, 3, s12
	s_sub_i32 s49, 39, s12
	s_cmp_lt_u32 s12, 4
	s_cselect_b32 s48, s48, s49
	s_cmp_eq_u32 s31, 0
	s_cselect_b32 s54, s12, s48
	s_lshl_b32 s48, s54, 6
	s_add_i32 s49, s33, s48
	s_add_i32 s48, s34, s48
	s_cmp_lt_u32 s54, 4
	s_cselect_b32 s55, s49, s48
	s_add_i32 s48, s55, 16
	s_add_i32 s49, s55, 32
	s_cmp_eq_u32 s31, 0
	s_cselect_b32 s48, s48, s49
	s_lshl_b32 s48, s48, 11
	s_add_u32 s8, s28, s48
	s_addc_u32 s9, s29, 0
	s_add_i32 s48, s55, 32
	s_add_i32 s49, s55, 16
	s_cmp_eq_u32 s31, 0
	s_cselect_b32 s48, s48, s49
	s_lshl_b32 s48, s48, 11
	s_add_u32 s10, s28, s48
	s_addc_u32 s11, s29, 0
	v_cvt_pk_bf16_f32 v150, v2, v3
	v_cvt_pk_bf16_f32 v151, v4, v5
	v_cvt_pk_bf16_f32 v152, v6, v7
	v_cvt_pk_bf16_f32 v153, v8, v9
	v_cvt_pk_bf16_f32 v154, v10, v11
	v_cvt_pk_bf16_f32 v155, v12, v13
	v_cvt_pk_bf16_f32 v156, v14, v15
	v_cvt_pk_bf16_f32 v157, v16, v17
	v_cvt_pk_bf16_f32 v158, v18, v19
	v_cvt_pk_bf16_f32 v159, v20, v21
	v_cvt_pk_bf16_f32 v160, v22, v23
	v_cvt_pk_bf16_f32 v161, v24, v25
	v_cvt_pk_bf16_f32 v162, v26, v27
	v_cvt_pk_bf16_f32 v163, v28, v29
	v_cvt_pk_bf16_f32 v164, v30, v31
	v_cvt_pk_bf16_f32 v165, v32, v33
	ds_read_b64_tr_b16 v[126:127], v184 offset:35840
	ds_read_b64_tr_b16 v[128:129], v184 offset:38400
	ds_read_b64_tr_b16 v[130:131], v184 offset:40960
	ds_read_b64_tr_b16 v[132:133], v184 offset:43520
	ds_read_b64_tr_b16 v[62:63], v185 offset:17408
	ds_read_b64_tr_b16 v[64:65], v185 offset:22016
	ds_read_b64_tr_b16 v[66:67], v185 offset:26624
	ds_read_b64_tr_b16 v[68:69], v185 offset:31232
	ds_read_b64_tr_b16 v[70:71], v185 offset:17440
	ds_read_b64_tr_b16 v[72:73], v185 offset:22048
	ds_read_b64_tr_b16 v[74:75], v185 offset:26656
	ds_read_b64_tr_b16 v[76:77], v185 offset:31264
	ds_read_b64_tr_b16 v[78:79], v185 offset:17472
	ds_read_b64_tr_b16 v[80:81], v185 offset:22080
	ds_read_b64_tr_b16 v[82:83], v185 offset:26688
	ds_read_b64_tr_b16 v[84:85], v185 offset:31296
	ds_read_b64_tr_b16 v[86:87], v185 offset:17504
	ds_read_b64_tr_b16 v[88:89], v185 offset:22112
	ds_read_b64_tr_b16 v[90:91], v185 offset:26720
	ds_read_b64_tr_b16 v[92:93], v185 offset:31328
	ds_read_b64 v[94:95], v183 offset:4352
	ds_read_b64 v[96:97], v183 offset:4384
	ds_read_b64 v[98:99], v183 offset:4416
	ds_read_b64 v[100:101], v183 offset:4448
	ds_read_b64 v[102:103], v183 offset:4480
	ds_read_b64 v[104:105], v183 offset:4512
	ds_read_b64 v[106:107], v183 offset:4544
	ds_read_b64 v[108:109], v183 offset:4576
	ds_read_b64 v[110:111], v183 offset:8704
	ds_read_b64 v[112:113], v183 offset:8736
	ds_read_b64 v[114:115], v183 offset:8768
	ds_read_b64 v[116:117], v183 offset:8800
	ds_read_b64 v[118:119], v183 offset:8832
	ds_read_b64 v[120:121], v183 offset:8864
	ds_read_b64 v[122:123], v183 offset:8896
	ds_read_b64 v[124:125], v183 offset:8928
	s_barrier
	s_waitcnt lgkmcnt(15)
	v_mfma_f32_16x16x32_bf16 v[2:5], v[62:65], v[126:129], v[2:5]
	v_mfma_f32_16x16x32_bf16 v[2:5], v[66:69], v[130:133], v[2:5]
	v_mfma_f32_16x16x32_bf16 v[6:9], v[70:73], v[126:129], v[6:9]
	v_mfma_f32_16x16x32_bf16 v[6:9], v[74:77], v[130:133], v[6:9]
	v_mfma_f32_16x16x32_bf16 v[10:13], v[78:81], v[126:129], v[10:13]
	v_mfma_f32_16x16x32_bf16 v[10:13], v[82:85], v[130:133], v[10:13]
	v_mfma_f32_16x16x32_bf16 v[14:17], v[86:89], v[126:129], v[14:17]
	v_mfma_f32_16x16x32_bf16 v[14:17], v[90:93], v[130:133], v[14:17]
	s_waitcnt lgkmcnt(0)
	v_mfma_f32_16x16x32_bf16 v[34:37], v[150:153], v[94:97], 0
	v_mfma_f32_16x16x32_bf16 v[38:41], v[150:153], v[110:113], 0
	v_mfma_f32_16x16x32_bf16 v[34:37], v[154:157], v[98:101], v[34:37]
	v_mfma_f32_16x16x32_bf16 v[38:41], v[154:157], v[114:117], v[38:41]
	v_mfma_f32_16x16x32_bf16 v[34:37], v[158:161], v[102:105], v[34:37]
	v_mfma_f32_16x16x32_bf16 v[38:41], v[158:161], v[118:121], v[38:41]
	v_mfma_f32_16x16x32_bf16 v[34:37], v[162:165], v[106:109], v[34:37]
	v_mfma_f32_16x16x32_bf16 v[38:41], v[162:165], v[122:125], v[38:41]
	ds_read_b128 v[62:65], v56 offset:0
	ds_read_b128 v[66:69], v56 offset:64
	ds_read_b128 v[70:73], v56 offset:128
	ds_read_b128 v[74:77], v56 offset:192
	ds_read_b128 v[166:169], v54 offset:17408
	ds_read_b128 v[170:173], v54 offset:17472
	ds_read_b128 v[174:177], v54 offset:17536
	ds_read_b128 v[178:181], v54 offset:17600
	ds_read_b128 v[200:203], v55 offset:17408
	ds_read_b128 v[204:207], v55 offset:17472
	ds_read_b128 v[208:211], v55 offset:17536
	ds_read_b128 v[212:215], v55 offset:17600
	s_cmp_gt_u32 s12, 5
	s_cbranch_scc1 .Lp8_w10_4
	s_waitcnt vmcnt(6)
	s_branch .Lp8_wd_4

.Lp8_wd_4:
	ds_write_b128 v243, v[142:145] offset:17408
	ds_write_b128 v243, v[146:149] offset:26624
	ds_write_b128 v190, v[238:241] offset:35840
	ds_write_b128 v189, v[134:137]
	ds_write_b128 v189, v[138:141] offset:8704
	ds_write_b32 v191, v237
	s_add_i32 s64, s12, 3
	s_min_u32 s65, s64, 35
	s_sub_i32 s48, 3, s65
	s_sub_i32 s49, 39, s65
	s_cmp_lt_u32 s65, 4
	s_cselect_b32 s48, s48, s49
	s_cmp_eq_u32 s31, 0
	s_cselect_b32 s54, s65, s48
	s_lshl_b32 s48, s54, 6
	s_add_i32 s49, s33, s48
	s_add_i32 s48, s34, s48
	s_cmp_lt_u32 s54, 4
	s_cselect_b32 s55, s49, s48
	s_mul_i32 s48, s55, s30
	s_add_u32 s0, s16, s48
	s_addc_u32 s1, s17, 0
	s_add_u32 s2, s18, s48
	s_addc_u32 s3, s19, 0
	s_mul_i32 s48, s55, 0x1800
	s_add_u32 s4, s20, s48
	s_addc_u32 s5, s21, 0
	s_lshl_b32 s48, s54, 9
	s_add_u32 s6, s22, s48
	s_addc_u32 s7, s23, 0
	global_load_dwordx4 v[142:145], v244, s[2:3]
	global_load_dwordx4 v[146:149], v245, s[2:3]
	global_load_dwordx4 v[238:241], v246, s[4:5]
	global_load_dwordx4 v[134:137], v244, s[0:1]
	global_load_dwordx4 v[138:141], v245, s[0:1]
	global_load_dword v237, v194, s[6:7]
	s_barrier
	s_waitcnt lgkmcnt(6)
	v_mfma_f32_16x16x32_bf16 v[42:45], v[166:169], v[62:65], 0
	v_mfma_f32_16x16x32_bf16 v[46:49], v[200:203], v[62:65], 0
	v_mfma_f32_16x16x32_bf16 v[42:45], v[170:173], v[66:69], v[42:45]
	v_mfma_f32_16x16x32_bf16 v[46:49], v[204:207], v[66:69], v[46:49]
	v_mfma_f32_16x16x32_bf16 v[42:45], v[174:177], v[70:73], v[42:45]
	v_mfma_f32_16x16x32_bf16 v[46:49], v[208:211], v[70:73], v[46:49]
	v_mfma_f32_16x16x32_bf16 v[42:45], v[178:181], v[74:77], v[42:45]
	v_mfma_f32_16x16x32_bf16 v[46:49], v[212:215], v[74:77], v[46:49]
	s_nop 6
	v_cndmask_b32_e64 v42, v42, 0, s[40:41]
	v_cndmask_b32_e64 v43, v43, 0, s[42:43]
	v_cndmask_b32_e64 v44, v44, 0, s[44:45]
	v_cndmask_b32_e64 v45, v45, 0, s[46:47]
	v_cndmask_b32_e64 v46, v46, 0, s[80:81]
	v_cndmask_b32_e64 v47, v47, 0, s[82:83]
	v_cndmask_b32_e64 v48, v48, 0, s[84:85]
	v_cndmask_b32_e64 v49, v49, 0, s[86:87]
	v_cvt_pk_bf16_f32 v50, v42, v43
	v_cvt_pk_bf16_f32 v51, v44, v45
	v_cvt_pk_bf16_f32 v52, v46, v47
	v_cvt_pk_bf16_f32 v53, v48, v49
	ds_write_b64 v57, v[50:51]
	ds_write_b64 v58, v[52:53]
	ds_read_b64_tr_b16 v[62:63], v185 offset:17536
	ds_read_b64_tr_b16 v[64:65], v185 offset:22144
	ds_read_b64_tr_b16 v[66:67], v185 offset:26752
	ds_read_b64_tr_b16 v[68:69], v185 offset:31360
	ds_read_b64_tr_b16 v[70:71], v185 offset:17568
	ds_read_b64_tr_b16 v[72:73], v185 offset:22176
	ds_read_b64_tr_b16 v[74:75], v185 offset:26784
	ds_read_b64_tr_b16 v[76:77], v185 offset:31392
	ds_read_b64_tr_b16 v[78:79], v185 offset:17600
	ds_read_b64_tr_b16 v[80:81], v185 offset:22208
	ds_read_b64_tr_b16 v[82:83], v185 offset:26816
	ds_read_b64_tr_b16 v[84:85], v185 offset:31424
	ds_read_b64_tr_b16 v[86:87], v185 offset:17632
	ds_read_b64_tr_b16 v[88:89], v185 offset:22240
	ds_read_b64_tr_b16 v[90:91], v185 offset:26848
	ds_read_b64_tr_b16 v[92:93], v185 offset:31456
	ds_read_b128 v[166:169], v188 offset:0
	ds_read_b128 v[170:173], v188 offset:64
	ds_read_b128 v[174:177], v188 offset:128
	ds_read_b128 v[178:181], v188 offset:192
	ds_read_b128 v[200:203], v188 offset:256
	ds_read_b128 v[204:207], v188 offset:320
	ds_read_b128 v[208:211], v188 offset:384
	ds_read_b128 v[212:215], v188 offset:448
	s_mov_b64 s[76:77], s[8:9]
	s_mov_b64 s[78:79], s[10:11]
	s_waitcnt lgkmcnt(15)
	s_barrier
.Lp8_next_0:
	s_add_i32 s12, s12, 1
	v_add_u32_e32 v182, 0xb400, v182
	v_add_u32_e32 v183, 0xb400, v183
	v_add_u32_e32 v184, 0xb400, v184
	v_add_u32_e32 v185, 0xb400, v185
	v_add_u32_e32 v242, 0xb400, v242
	v_add_u32_e32 v54, 0xb400, v54
	v_add_u32_e32 v55, 0xb400, v55
	v_add_u32_e32 v56, 0xb400, v56
	v_add_u32_e32 v189, 0xffff4c00, v189
	v_add_u32_e32 v243, 0xffff4c00, v243
	v_add_u32_e32 v190, 0xffff4c00, v190
	v_add_u32_e32 v188, 0x200, v188
	v_add_u32_e32 v191, 0xfffffe00, v191
	s_cmp_lt_u32 s12, 4
	s_nop 0
	s_cbranch_scc0 .Lp8_lat_1
	ds_read_b64_tr_b16 v[126:127], v184 offset:35840
	ds_read_b64_tr_b16 v[128:129], v184 offset:38400
	ds_read_b64_tr_b16 v[130:131], v184 offset:40960
	ds_read_b64_tr_b16 v[132:133], v184 offset:43520
	ds_read_b64_tr_b16 v[62:63], v185 offset:17408
	ds_read_b64_tr_b16 v[64:65], v185 offset:22016
	ds_read_b64_tr_b16 v[66:67], v185 offset:26624
	ds_read_b64_tr_b16 v[68:69], v185 offset:31232
	ds_read_b64_tr_b16 v[70:71], v185 offset:17440
	ds_read_b64_tr_b16 v[72:73], v185 offset:22048
	ds_read_b64_tr_b16 v[74:75], v185 offset:26656
	ds_read_b64_tr_b16 v[76:77], v185 offset:31264
	ds_read_b64_tr_b16 v[78:79], v185 offset:17472
	ds_read_b64_tr_b16 v[80:81], v185 offset:22080
	ds_read_b64_tr_b16 v[82:83], v185 offset:26688
	ds_read_b64_tr_b16 v[84:85], v185 offset:31296
	ds_read_b64_tr_b16 v[86:87], v185 offset:17504
	ds_read_b64_tr_b16 v[88:89], v185 offset:22112
	ds_read_b64_tr_b16 v[90:91], v185 offset:26720
	ds_read_b64_tr_b16 v[92:93], v185 offset:31328
	ds_read_b64_tr_b16 v[94:95], v185 offset:17536
	ds_read_b64_tr_b16 v[96:97], v185 offset:22144
	ds_read_b64_tr_b16 v[98:99], v185 offset:26752
	ds_read_b64_tr_b16 v[100:101], v185 offset:31360
	ds_read_b64_tr_b16 v[102:103], v185 offset:17568
	ds_read_b64_tr_b16 v[104:105], v185 offset:22176
	ds_read_b64_tr_b16 v[106:107], v185 offset:26784
	ds_read_b64_tr_b16 v[108:109], v185 offset:31392
	ds_read_b64_tr_b16 v[110:111], v185 offset:17600
	ds_read_b64_tr_b16 v[112:113], v185 offset:22208
	ds_read_b64_tr_b16 v[114:115], v185 offset:26816
	ds_read_b64_tr_b16 v[116:117], v185 offset:31424
	ds_read_b64_tr_b16 v[118:119], v185 offset:17632
	ds_read_b64_tr_b16 v[120:121], v185 offset:22240
	ds_read_b64_tr_b16 v[122:123], v185 offset:26848
	ds_read_b64_tr_b16 v[124:125], v185 offset:31456
	ds_read_b128 v[166:169], v188 offset:0
	ds_read_b128 v[170:173], v188 offset:64
	ds_read_b128 v[174:177], v188 offset:128
	ds_read_b128 v[178:181], v188 offset:192
	ds_read_b128 v[200:203], v188 offset:256
	ds_read_b128 v[204:207], v188 offset:320
	ds_read_b128 v[208:211], v188 offset:384
	ds_read_b128 v[212:215], v188 offset:448
	s_waitcnt vmcnt(6)
	ds_write_b128 v243, v[224:227] offset:17408
	ds_write_b128 v243, v[228:231] offset:26624
	ds_write_b128 v190, v[232:235] offset:35840
	ds_write_b128 v189, v[216:219]
	ds_write_b128 v189, v[220:223] offset:8704
	ds_write_b32 v191, v236
	s_add_i32 s64, s12, 3
	s_min_u32 s65, s64, 35
	s_sub_i32 s48, 3, s65
	s_sub_i32 s49, 39, s65
	s_cmp_lt_u32 s65, 4
	s_cselect_b32 s48, s48, s49
	s_cmp_eq_u32 s31, 0
	s_cselect_b32 s54, s65, s48
	s_lshl_b32 s48, s54, 6
	s_add_i32 s49, s33, s48
	s_add_i32 s48, s34, s48
	s_cmp_lt_u32 s54, 4
	s_cselect_b32 s55, s49, s48
	s_mul_i32 s48, s55, s30
	s_add_u32 s0, s16, s48
	s_addc_u32 s1, s17, 0
	s_add_u32 s2, s18, s48
	s_addc_u32 s3, s19, 0
	s_mul_i32 s48, s55, 0x1800
	s_add_u32 s4, s20, s48
	s_addc_u32 s5, s21, 0
	s_lshl_b32 s48, s54, 9
	s_add_u32 s6, s22, s48
	s_addc_u32 s7, s23, 0
	global_load_dwordx4 v[224:227], v244, s[2:3]
	global_load_dwordx4 v[228:231], v245, s[2:3]
	global_load_dwordx4 v[232:235], v246, s[4:5]
	global_load_dwordx4 v[216:219], v244, s[0:1]
	global_load_dwordx4 v[220:223], v245, s[0:1]
	global_load_dword v236, v194, s[6:7]
	s_waitcnt lgkmcnt(15)
	v_mfma_f32_16x16x32_bf16 v[2:5], v[62:65], v[126:129], v[2:5]
	v_mfma_f32_16x16x32_bf16 v[2:5], v[66:69], v[130:133], v[2:5]
	v_mfma_f32_16x16x32_bf16 v[6:9], v[70:73], v[126:129], v[6:9]
	v_mfma_f32_16x16x32_bf16 v[6:9], v[74:77], v[130:133], v[6:9]
	v_mfma_f32_16x16x32_bf16 v[10:13], v[78:81], v[126:129], v[10:13]
	v_mfma_f32_16x16x32_bf16 v[10:13], v[82:85], v[130:133], v[10:13]
	v_mfma_f32_16x16x32_bf16 v[14:17], v[86:89], v[126:129], v[14:17]
	v_mfma_f32_16x16x32_bf16 v[14:17], v[90:93], v[130:133], v[14:17]
	s_waitcnt lgkmcnt(14)
	v_mfma_f32_16x16x32_bf16 v[18:21], v[94:97], v[126:129], v[18:21]
	v_mfma_f32_16x16x32_bf16 v[18:21], v[98:101], v[130:133], v[18:21]
	v_mfma_f32_16x16x32_bf16 v[22:25], v[102:105], v[126:129], v[22:25]
	v_mfma_f32_16x16x32_bf16 v[22:25], v[106:109], v[130:133], v[22:25]
	v_mfma_f32_16x16x32_bf16 v[26:29], v[110:113], v[126:129], v[26:29]
	v_mfma_f32_16x16x32_bf16 v[26:29], v[114:117], v[130:133], v[26:29]
	v_mfma_f32_16x16x32_bf16 v[30:33], v[118:121], v[126:129], v[30:33]
	v_mfma_f32_16x16x32_bf16 v[30:33], v[122:125], v[130:133], v[30:33]
	s_waitcnt lgkmcnt(0)
	v_pk_mul_f32 v[2:3], v[2:3], v[166:167]
	v_pk_mul_f32 v[4:5], v[4:5], v[168:169]
	v_pk_mul_f32 v[6:7], v[6:7], v[170:171]
	v_pk_mul_f32 v[8:9], v[8:9], v[172:173]
	v_pk_mul_f32 v[10:11], v[10:11], v[174:175]
	v_pk_mul_f32 v[12:13], v[12:13], v[176:177]
	v_pk_mul_f32 v[14:15], v[14:15], v[178:179]
	v_pk_mul_f32 v[16:17], v[16:17], v[180:181]
	v_pk_mul_f32 v[18:19], v[18:19], v[200:201]
	v_pk_mul_f32 v[20:21], v[20:21], v[202:203]
	v_pk_mul_f32 v[22:23], v[22:23], v[204:205]
	v_pk_mul_f32 v[24:25], v[24:25], v[206:207]
	v_pk_mul_f32 v[26:27], v[26:27], v[208:209]
	v_pk_mul_f32 v[28:29], v[28:29], v[210:211]
	v_pk_mul_f32 v[30:31], v[30:31], v[212:213]
	v_pk_mul_f32 v[32:33], v[32:33], v[214:215]
	s_nop 1
	s_barrier
	s_branch .Lp8_next_1

.Lp8_wd_6:
	ds_write_b128 v243, v[224:227] offset:17408
	ds_write_b128 v243, v[228:231] offset:26624
	ds_write_b128 v190, v[232:235] offset:35840
	ds_write_b128 v189, v[216:219]
	ds_write_b128 v189, v[220:223] offset:8704
	ds_write_b32 v191, v236
	s_add_i32 s64, s12, 3
	s_min_u32 s65, s64, 35
	s_sub_i32 s48, 3, s65
	s_sub_i32 s49, 39, s65
	s_cmp_lt_u32 s65, 4
	s_cselect_b32 s48, s48, s49
	s_cmp_eq_u32 s31, 0
	s_cselect_b32 s54, s65, s48
	s_lshl_b32 s48, s54, 6
	s_add_i32 s49, s33, s48
	s_add_i32 s48, s34, s48
	s_cmp_lt_u32 s54, 4
	s_cselect_b32 s55, s49, s48
	s_mul_i32 s48, s55, s30
	s_add_u32 s0, s16, s48
	s_addc_u32 s1, s17, 0
	s_add_u32 s2, s18, s48
	s_addc_u32 s3, s19, 0
	s_mul_i32 s48, s55, 0x1800
	s_add_u32 s4, s20, s48
	s_addc_u32 s5, s21, 0
	s_lshl_b32 s48, s54, 9
	s_add_u32 s6, s22, s48
	s_addc_u32 s7, s23, 0
	global_load_dwordx4 v[224:227], v244, s[2:3]
	global_load_dwordx4 v[228:231], v245, s[2:3]
	global_load_dwordx4 v[232:235], v246, s[4:5]
	global_load_dwordx4 v[216:219], v244, s[0:1]
	global_load_dwordx4 v[220:223], v245, s[0:1]
	global_load_dword v236, v194, s[6:7]
	s_waitcnt lgkmcnt(6)
	v_mfma_f32_16x16x32_bf16 v[42:45], v[166:169], v[62:65], 0
	v_mfma_f32_16x16x32_bf16 v[46:49], v[200:203], v[62:65], 0
	v_mfma_f32_16x16x32_bf16 v[42:45], v[170:173], v[66:69], v[42:45]
	v_mfma_f32_16x16x32_bf16 v[46:49], v[204:207], v[66:69], v[46:49]
	v_mfma_f32_16x16x32_bf16 v[42:45], v[174:177], v[70:73], v[42:45]
	v_mfma_f32_16x16x32_bf16 v[46:49], v[208:211], v[70:73], v[46:49]
	v_mfma_f32_16x16x32_bf16 v[42:45], v[178:181], v[74:77], v[42:45]
	v_mfma_f32_16x16x32_bf16 v[46:49], v[212:215], v[74:77], v[46:49]
	s_nop 6
	v_cndmask_b32_e64 v42, v42, 0, s[40:41]
	v_cndmask_b32_e64 v43, v43, 0, s[42:43]
	v_cndmask_b32_e64 v44, v44, 0, s[44:45]
	v_cndmask_b32_e64 v45, v45, 0, s[46:47]
	v_cndmask_b32_e64 v46, v46, 0, s[80:81]
	v_cndmask_b32_e64 v47, v47, 0, s[82:83]
	v_cndmask_b32_e64 v48, v48, 0, s[84:85]
	v_cndmask_b32_e64 v49, v49, 0, s[86:87]
	v_cvt_pk_bf16_f32 v50, v42, v43
	v_cvt_pk_bf16_f32 v51, v44, v45
	v_cvt_pk_bf16_f32 v52, v46, v47
	v_cvt_pk_bf16_f32 v53, v48, v49
	ds_write_b64 v57, v[50:51]
	ds_write_b64 v58, v[52:53]
	s_waitcnt lgkmcnt(0)
	s_barrier
	ds_read_b64_tr_b16 v[62:63], v185 offset:17536
	ds_read_b64_tr_b16 v[64:65], v185 offset:22144
	ds_read_b64_tr_b16 v[66:67], v185 offset:26752
	ds_read_b64_tr_b16 v[68:69], v185 offset:31360
	ds_read_b64_tr_b16 v[70:71], v185 offset:17568
	ds_read_b64_tr_b16 v[72:73], v185 offset:22176
	ds_read_b64_tr_b16 v[74:75], v185 offset:26784
	ds_read_b64_tr_b16 v[76:77], v185 offset:31392
	ds_read_b64_tr_b16 v[78:79], v185 offset:17600
	ds_read_b64_tr_b16 v[80:81], v185 offset:22208
	ds_read_b64_tr_b16 v[82:83], v185 offset:26816
	ds_read_b64_tr_b16 v[84:85], v185 offset:31424
	ds_read_b64_tr_b16 v[86:87], v185 offset:17632
	ds_read_b64_tr_b16 v[88:89], v185 offset:22240
	ds_read_b64_tr_b16 v[90:91], v185 offset:26848
	ds_read_b64_tr_b16 v[92:93], v185 offset:31456
	ds_read_b128 v[150:153], v59 offset:0
	ds_read_b128 v[154:157], v59 offset:7680
	ds_read_b128 v[158:161], v59 offset:7744
	ds_read_b128 v[166:169], v188 offset:0
	ds_read_b128 v[170:173], v188 offset:64
	ds_read_b128 v[174:177], v188 offset:128
	ds_read_b128 v[178:181], v188 offset:192
	ds_read_b128 v[200:203], v188 offset:256
	ds_read_b128 v[204:207], v188 offset:320
	ds_read_b128 v[208:211], v188 offset:384
	ds_read_b128 v[212:215], v188 offset:448
	s_waitcnt lgkmcnt(11)
	v_mfma_f32_16x16x32_bf16 v[18:21], v[62:65], v[126:129], v[18:21]
	v_mfma_f32_16x16x32_bf16 v[18:21], v[66:69], v[130:133], v[18:21]
	v_mfma_f32_16x16x32_bf16 v[22:25], v[70:73], v[126:129], v[22:25]
	v_mfma_f32_16x16x32_bf16 v[22:25], v[74:77], v[130:133], v[22:25]
	v_mfma_f32_16x16x32_bf16 v[26:29], v[78:81], v[126:129], v[26:29]
	v_mfma_f32_16x16x32_bf16 v[26:29], v[82:85], v[130:133], v[26:29]
	v_mfma_f32_16x16x32_bf16 v[30:33], v[86:89], v[126:129], v[30:33]
	v_mfma_f32_16x16x32_bf16 v[30:33], v[90:93], v[130:133], v[30:33]
	s_waitcnt lgkmcnt(8)
	v_mfma_f32_16x16x32_bf16 v[34:37], v[126:129], v[150:153], v[34:37]
	v_mfma_f32_16x16x32_bf16 v[38:41], v[126:129], v[154:157], v[38:41]
	v_mfma_f32_16x16x32_bf16 v[38:41], v[130:133], v[158:161], v[38:41]
	s_waitcnt lgkmcnt(0)
	v_pk_mul_f32 v[2:3], v[2:3], v[166:167]
	v_pk_mul_f32 v[4:5], v[4:5], v[168:169]
	v_pk_mul_f32 v[6:7], v[6:7], v[170:171]
	v_pk_mul_f32 v[8:9], v[8:9], v[172:173]
	v_pk_mul_f32 v[10:11], v[10:11], v[174:175]
	v_pk_mul_f32 v[12:13], v[12:13], v[176:177]
	v_pk_mul_f32 v[14:15], v[14:15], v[178:179]
	v_pk_mul_f32 v[16:17], v[16:17], v[180:181]
	v_pk_mul_f32 v[18:19], v[18:19], v[200:201]
	v_pk_mul_f32 v[20:21], v[20:21], v[202:203]
	v_pk_mul_f32 v[22:23], v[22:23], v[204:205]
	v_pk_mul_f32 v[24:25], v[24:25], v[206:207]
	v_pk_mul_f32 v[26:27], v[26:27], v[208:209]
	v_pk_mul_f32 v[28:29], v[28:29], v[210:211]
	v_pk_mul_f32 v[30:31], v[30:31], v[212:213]
	v_pk_mul_f32 v[32:33], v[32:33], v[214:215]
	v_cvt_pk_bf16_f32 v50, v34, v35
	v_cvt_pk_bf16_f32 v51, v36, v37
	global_store_dwordx2 v247, v[50:51], s[8:9]
	v_cvt_pk_bf16_f32 v52, v38, v39
	v_cvt_pk_bf16_f32 v53, v40, v41
	global_store_dwordx2 v247, v[52:53], s[10:11]
	s_nop 0
	s_barrier
	s_branch .Lp8_next_1

.Lp8_wd_8:
	ds_write_b128 v243, v[224:227] offset:17408
	ds_write_b128 v243, v[228:231] offset:26624
	ds_write_b128 v190, v[232:235] offset:35840
	ds_write_b128 v189, v[216:219]
	ds_write_b128 v189, v[220:223] offset:8704
	ds_write_b32 v191, v236
	s_add_i32 s64, s12, 3
	s_min_u32 s65, s64, 35
	s_sub_i32 s48, 3, s65
	s_sub_i32 s49, 39, s65
	s_cmp_lt_u32 s65, 4
	s_cselect_b32 s48, s48, s49
	s_cmp_eq_u32 s31, 0
	s_cselect_b32 s54, s65, s48
	s_lshl_b32 s48, s54, 6
	s_add_i32 s49, s33, s48
	s_add_i32 s48, s34, s48
	s_cmp_lt_u32 s54, 4
	s_cselect_b32 s55, s49, s48
	s_mul_i32 s48, s55, s30
	s_add_u32 s0, s16, s48
	s_addc_u32 s1, s17, 0
	s_add_u32 s2, s18, s48
	s_addc_u32 s3, s19, 0
	s_mul_i32 s48, s55, 0x1800
	s_add_u32 s4, s20, s48
	s_addc_u32 s5, s21, 0
	s_lshl_b32 s48, s54, 9
	s_add_u32 s6, s22, s48
	s_addc_u32 s7, s23, 0
	global_load_dwordx4 v[224:227], v244, s[2:3]
	global_load_dwordx4 v[228:231], v245, s[2:3]
	global_load_dwordx4 v[232:235], v246, s[4:5]
	global_load_dwordx4 v[216:219], v244, s[0:1]
	global_load_dwordx4 v[220:223], v245, s[0:1]
	global_load_dword v236, v194, s[6:7]
	s_barrier
	s_waitcnt lgkmcnt(6)
	v_mfma_f32_16x16x32_bf16 v[42:45], v[166:169], v[62:65], 0
	v_mfma_f32_16x16x32_bf16 v[46:49], v[200:203], v[62:65], 0
	v_mfma_f32_16x16x32_bf16 v[42:45], v[170:173], v[66:69], v[42:45]
	v_mfma_f32_16x16x32_bf16 v[46:49], v[204:207], v[66:69], v[46:49]
	v_mfma_f32_16x16x32_bf16 v[42:45], v[174:177], v[70:73], v[42:45]
	v_mfma_f32_16x16x32_bf16 v[46:49], v[208:211], v[70:73], v[46:49]
	v_mfma_f32_16x16x32_bf16 v[42:45], v[178:181], v[74:77], v[42:45]
	v_mfma_f32_16x16x32_bf16 v[46:49], v[212:215], v[74:77], v[46:49]
	s_nop 6
	v_cndmask_b32_e64 v42, v42, 0, s[40:41]
	v_cndmask_b32_e64 v43, v43, 0, s[42:43]
	v_cndmask_b32_e64 v44, v44, 0, s[44:45]
	v_cndmask_b32_e64 v45, v45, 0, s[46:47]
	v_cndmask_b32_e64 v46, v46, 0, s[80:81]
	v_cndmask_b32_e64 v47, v47, 0, s[82:83]
	v_cndmask_b32_e64 v48, v48, 0, s[84:85]
	v_cndmask_b32_e64 v49, v49, 0, s[86:87]
	v_cvt_pk_bf16_f32 v50, v42, v43
	v_cvt_pk_bf16_f32 v51, v44, v45
	v_cvt_pk_bf16_f32 v52, v46, v47
	v_cvt_pk_bf16_f32 v53, v48, v49
	ds_write_b64 v57, v[50:51]
	ds_write_b64 v58, v[52:53]
	ds_read_b64_tr_b16 v[62:63], v185 offset:17536
	ds_read_b64_tr_b16 v[64:65], v185 offset:22144
	ds_read_b64_tr_b16 v[66:67], v185 offset:26752
	ds_read_b64_tr_b16 v[68:69], v185 offset:31360
	ds_read_b64_tr_b16 v[70:71], v185 offset:17568
	ds_read_b64_tr_b16 v[72:73], v185 offset:22176
	ds_read_b64_tr_b16 v[74:75], v185 offset:26784
	ds_read_b64_tr_b16 v[76:77], v185 offset:31392
	ds_read_b64_tr_b16 v[78:79], v185 offset:17600
	ds_read_b64_tr_b16 v[80:81], v185 offset:22208
	ds_read_b64_tr_b16 v[82:83], v185 offset:26816
	ds_read_b64_tr_b16 v[84:85], v185 offset:31424
	ds_read_b64_tr_b16 v[86:87], v185 offset:17632
	ds_read_b64_tr_b16 v[88:89], v185 offset:22240
	ds_read_b64_tr_b16 v[90:91], v185 offset:26848
	ds_read_b64_tr_b16 v[92:93], v185 offset:31456
	ds_read_b128 v[166:169], v188 offset:0
	ds_read_b128 v[170:173], v188 offset:64
	ds_read_b128 v[174:177], v188 offset:128
	ds_read_b128 v[178:181], v188 offset:192
	ds_read_b128 v[200:203], v188 offset:256
	ds_read_b128 v[204:207], v188 offset:320
	ds_read_b128 v[208:211], v188 offset:384
	ds_read_b128 v[212:215], v188 offset:448
	s_mov_b64 s[76:77], s[8:9]
	s_mov_b64 s[78:79], s[10:11]
	s_waitcnt lgkmcnt(15)
	s_barrier
.Lp8_next_1:
	s_add_i32 s12, s12, 1
	s_cmp_lt_u32 s12, 36
	s_cbranch_scc1 .Lp8_step
	s_cmp_eq_u32 s37, 0
	s_cbranch_scc1 .Lp8_done
	ds_read_b128 v[150:153], v59 offset:2560
	ds_read_b128 v[154:157], v59 offset:5120
	ds_read_b128 v[158:161], v59 offset:5184
	s_waitcnt lgkmcnt(11)
	v_mfma_f32_16x16x32_bf16 v[18:21], v[62:65], v[126:129], v[18:21]
	v_mfma_f32_16x16x32_bf16 v[18:21], v[66:69], v[130:133], v[18:21]
	v_mfma_f32_16x16x32_bf16 v[22:25], v[70:73], v[126:129], v[22:25]
	v_mfma_f32_16x16x32_bf16 v[22:25], v[74:77], v[130:133], v[22:25]
	v_mfma_f32_16x16x32_bf16 v[26:29], v[78:81], v[126:129], v[26:29]
	v_mfma_f32_16x16x32_bf16 v[26:29], v[82:85], v[130:133], v[26:29]
	v_mfma_f32_16x16x32_bf16 v[30:33], v[86:89], v[126:129], v[30:33]
	v_mfma_f32_16x16x32_bf16 v[30:33], v[90:93], v[130:133], v[30:33]
	s_waitcnt lgkmcnt(0)
	v_mfma_f32_16x16x32_bf16 v[34:37], v[126:129], v[150:153], v[34:37]
	v_mfma_f32_16x16x32_bf16 v[38:41], v[126:129], v[154:157], v[38:41]
	v_mfma_f32_16x16x32_bf16 v[38:41], v[130:133], v[158:161], v[38:41]
	v_pk_mul_f32 v[2:3], v[2:3], v[166:167]
	v_pk_mul_f32 v[4:5], v[4:5], v[168:169]
	v_pk_mul_f32 v[6:7], v[6:7], v[170:171]
	v_pk_mul_f32 v[8:9], v[8:9], v[172:173]
	v_pk_mul_f32 v[10:11], v[10:11], v[174:175]
	v_pk_mul_f32 v[12:13], v[12:13], v[176:177]
	v_pk_mul_f32 v[14:15], v[14:15], v[178:179]
	v_pk_mul_f32 v[16:17], v[16:17], v[180:181]
	v_pk_mul_f32 v[18:19], v[18:19], v[200:201]
	v_pk_mul_f32 v[20:21], v[20:21], v[202:203]
	v_pk_mul_f32 v[22:23], v[22:23], v[204:205]
	v_pk_mul_f32 v[24:25], v[24:25], v[206:207]
	v_pk_mul_f32 v[26:27], v[26:27], v[208:209]
	v_pk_mul_f32 v[28:29], v[28:29], v[210:211]
	v_pk_mul_f32 v[30:31], v[30:31], v[212:213]
	v_pk_mul_f32 v[32:33], v[32:33], v[214:215]
	v_cvt_pk_bf16_f32 v50, v34, v35
	v_cvt_pk_bf16_f32 v51, v36, v37
	global_store_dwordx2 v247, v[50:51], s[76:77]
	v_cvt_pk_bf16_f32 v52, v38, v39
	v_cvt_pk_bf16_f32 v53, v40, v41
	global_store_dwordx2 v247, v[52:53], s[78:79]
	s_nop 0
